# v1 + attention K/V staging loads batched, LRU segment scan loads batched, LRU gate-weight image fetched in one round trip
# speedup vs baseline: 1.0062x; 1.0062x over previous
; #define LAS __attribute__((address_space(3)))
; __device__ __forceinline__ unsigned cvt_pk_bf16(float lo, float hi) { unsigned r; asm volatile("v_cvt_pk_bf16_f32 %0, %1, %2" : "=v"(r) : "v"(lo), "v"(hi)); return r; }
; __device__ __forceinline__ void attn_item(const Params& p, LAS unsigned char* L, int item, bf16_t* Yd, int ldd) {
;     ...
;     for (int i = 0; i < 3; ++i) {
;         const int idx = tid + i * 512, key = idx >> 3, dg = idx & 7;
;         u32x4 kv = {0u, 0u, 0u, 0u}, vv = {0u, 0u, 0u, 0u};
;         if (!smp) {
;             const int pos = c * 64 - 128 + key;
;             if (pos >= 0) { const size_t r = (size_t)b * 2048 + pos; kv = *(const u32x4*)(Kb + r * 256 + kh * 64 + dg * 8); vv = *(const u32x4*)(Vb + r * 256 + kh * 64 + dg * 8); }
;         } else {
;             if (key < 128) {
;                 const size_t o = ((size_t)(b * 128 + key) * 4 + kh) * 64 + dg * 8;
;                 const f32x4 k0 = *(const f32x4*)(p.in[2] + o), k1 = *(const f32x4*)(p.in[2] + o + 4), v0 = *(const f32x4*)(p.in[3] + o), v1 = *(const f32x4*)(p.in[3] + o + 4);
;                 kv.x = cvt_pk_bf16(k0[0], k0[1]); kv.y = cvt_pk_bf16(k0[2], k0[3]); kv.z = cvt_pk_bf16(k1[0], k1[1]); kv.w = cvt_pk_bf16(k1[2], k1[3]);
;                 vv.x = cvt_pk_bf16(v0[0], v0[1]); vv.y = cvt_pk_bf16(v0[2], v0[3]); vv.z = cvt_pk_bf16(v1[0], v1[1]); vv.w = cvt_pk_bf16(v1[2], v1[3]);
;             } else { const size_t r = (size_t)T_P + b * 64 + key - 128; kv = *(const u32x4*)(Kb + r * 256 + kh * 64 + dg * 8); vv = *(const u32x4*)(Vb + r * 256 + kh * 64 + dg * 8); }
;         }
;         *(LAS u32x4*)(Ks + key * 72 + dg * 8) = kv;
;         *(LAS u32x4*)(Vs + key * 72 + dg * 8) = vv;
;     }
.LBB0_316:
	s_lshl_b32 s52, s13, 7
	s_lshl_b32 s13, s12, 6
	v_lshl_add_u64 v[26:27], v[62:63], 0, s[52:53]
	v_lshl_add_u64 v[24:25], v[64:65], 0, s[52:53]
	s_add_i32 s14, s13, 0xffffff80
	s_andn2_b64 vcc, exec, s[8:9]
	s_lshl_b64 s[0:1], s[0:1], 19
	s_cbranch_vccnz .LBB0_320
	v_add_u32_e32 v54, s14, v104
	v_add_u32_e32 v30, s14, v56
	v_mov_b32_e32 v31, v55
	v_mov_b32_e32 v32, 0
	v_mov_b32_e32 v33, 0
	v_mov_b32_e32 v34, 0
	v_mov_b32_e32 v35, 0
	v_mov_b32_e32 v36, 0
	v_mov_b32_e32 v37, 0
	v_mov_b32_e32 v38, 0
	v_mov_b32_e32 v39, 0
	v_mov_b32_e32 v40, 0
	v_mov_b32_e32 v41, 0
	v_mov_b32_e32 v42, 0
	v_mov_b32_e32 v43, 0
	v_mov_b32_e32 v44, 0
	v_mov_b32_e32 v45, 0
	v_mov_b32_e32 v46, 0
	v_mov_b32_e32 v47, 0
	v_cmp_lt_i32_e32 vcc, -1, v54
	s_and_saveexec_b64 s[8:9], vcc
	s_cbranch_execz .Lattn_ps1
	v_lshlrev_b64 v[48:49], 8, v[54:55]
	v_lshl_add_u64 v[48:49], v[48:49], 0, s[0:1]
	v_lshlrev_b64 v[48:49], 1, v[48:49]
	v_lshl_add_u64 v[50:51], v[26:27], 0, v[48:49]
	v_lshl_add_u64 v[48:49], v[24:25], 0, v[48:49]
	global_load_dwordx4 v[32:35], v[50:51], off
	global_load_dwordx4 v[36:39], v[48:49], off
.Lattn_ps1:
	s_or_b64 exec, exec, s[8:9]
	v_cmp_lt_i32_e32 vcc, -1, v30
	s_and_saveexec_b64 s[8:9], vcc
	s_cbranch_execz .Lattn_ps2
	v_lshlrev_b64 v[48:49], 8, v[30:31]
	v_lshl_add_u64 v[48:49], v[48:49], 0, s[0:1]
	v_lshlrev_b64 v[48:49], 1, v[48:49]
	v_lshl_add_u64 v[50:51], v[26:27], 0, v[48:49]
	v_lshl_add_u64 v[48:49], v[24:25], 0, v[48:49]
	global_load_dwordx4 v[40:43], v[50:51], off
	global_load_dwordx4 v[44:47], v[48:49], off
.Lattn_ps2:
	s_or_b64 exec, exec, s[8:9]
	v_add_u32_e32 v30, s14, v58
	v_lshlrev_b64 v[48:49], 8, v[30:31]
	v_lshl_add_u64 v[48:49], v[48:49], 0, s[0:1]
	v_lshlrev_b64 v[48:49], 1, v[48:49]
	v_lshl_add_u64 v[50:51], v[26:27], 0, v[48:49]
	v_lshl_add_u64 v[48:49], v[24:25], 0, v[48:49]
	global_load_dwordx4 v[16:19], v[50:51], off
	global_load_dwordx4 v[20:23], v[48:49], off
	s_waitcnt vmcnt(2)
	ds_write_b128 v105, v[32:35]
	ds_write_b128 v105, v[36:39] offset:27648
	ds_write_b128 v106, v[40:43]
	ds_write_b128 v106, v[44:47] offset:27648
	s_branch .Lattn_i2_ready

; #define LAS __attribute__((address_space(3)))
; __device__ __forceinline__ unsigned cvt_pk_bf16(float lo, float hi) { unsigned r; asm volatile("v_cvt_pk_bf16_f32 %0, %1, %2" : "=v"(r) : "v"(lo), "v"(hi)); return r; }
; __device__ __forceinline__ void attn_item(const Params& p, LAS unsigned char* L, int item, bf16_t* Yd, int ldd) {
;     ...
;     for (int i = 0; i < 3; ++i) {
;         const int idx = tid + i * 512, key = idx >> 3, dg = idx & 7;
;         u32x4 kv = {0u, 0u, 0u, 0u}, vv = {0u, 0u, 0u, 0u};
;         if (!smp) {
;             const int pos = c * 64 - 128 + key;
;             if (pos >= 0) { const size_t r = (size_t)b * 2048 + pos; kv = *(const u32x4*)(Kb + r * 256 + kh * 64 + dg * 8); vv = *(const u32x4*)(Vb + r * 256 + kh * 64 + dg * 8); }
;         } else {
;             if (key < 128) {
;                 const size_t o = ((size_t)(b * 128 + key) * 4 + kh) * 64 + dg * 8;
;                 const f32x4 k0 = *(const f32x4*)(p.in[2] + o), k1 = *(const f32x4*)(p.in[2] + o + 4), v0 = *(const f32x4*)(p.in[3] + o), v1 = *(const f32x4*)(p.in[3] + o + 4);
;                 kv.x = cvt_pk_bf16(k0[0], k0[1]); kv.y = cvt_pk_bf16(k0[2], k0[3]); kv.z = cvt_pk_bf16(k1[0], k1[1]); kv.w = cvt_pk_bf16(k1[2], k1[3]);
;                 vv.x = cvt_pk_bf16(v0[0], v0[1]); vv.y = cvt_pk_bf16(v0[2], v0[3]); vv.z = cvt_pk_bf16(v1[0], v1[1]); vv.w = cvt_pk_bf16(v1[2], v1[3]);
;             } else { const size_t r = (size_t)T_P + b * 64 + key - 128; kv = *(const u32x4*)(Kb + r * 256 + kh * 64 + dg * 8); vv = *(const u32x4*)(Vb + r * 256 + kh * 64 + dg * 8); }
;         }
;         *(LAS u32x4*)(Ks + key * 72 + dg * 8) = kv;
;         *(LAS u32x4*)(Vs + key * 72 + dg * 8) = vv;
;     }
;     __syncthreads();
;     const float slope = exp2f(-0.5f * (float)(h + 1)) * 1.4426950408889634f;
;     const float sink = p.in[11][h] * 1.4426950408889634f;
;     const unsigned va = vbase + (unsigned)(((q4 * 4 + (r16 >> 2)) * 72 + 4 * (r16 & 3)) * 2);
.LBB0_326:
	s_andn2_b64 vcc, exec, s[10:11]
	s_movk_i32 s10, 0x8000
	s_mov_b32 s11, -1
	s_cbranch_vccnz .LBB0_330
.LBB0_330:
	s_waitcnt vmcnt(1)
	ds_write_b128 v106, v[16:19]
	s_waitcnt vmcnt(0)
	ds_write_b128 v106, v[20:23] offset:27648
	v_add_u32_e32 v18, s14, v58
	v_lshl_add_u64 v[16:17], s[8:9], 0, v[58:59]
	v_cndmask_b32_e64 v17, v17, 0, s[6:7]
	v_cndmask_b32_e64 v16, v16, v18, s[6:7]
	v_lshlrev_b64 v[16:17], 8, v[16:17]
	v_lshl_add_u64 v[16:17], s[10:11], 0, v[16:17]
	v_lshlrev_b64 v[20:21], 1, v[16:17]
	v_lshl_add_u64 v[16:17], v[26:27], 0, v[20:21]
	global_load_dwordx4 v[16:19], v[16:17], off
	v_lshl_add_u64 v[20:21], v[24:25], 0, v[20:21]
	global_load_dwordx4 v[20:23], v[20:21], off
.Lattn_i2_ready:
	s_mov_b32 s0, 0xc2fc0000
	v_readlane_b32 s16, v250, 20
	v_readlane_b32 s22, v250, 26
	v_readlane_b32 s23, v250, 27
	s_cmp_lt_u32 s12, 2
	v_lshlrev_b32_e32 v29, 6, v28
	v_readlane_b32 s18, v250, 22
	v_readlane_b32 s20, v250, 24
	v_readlane_b32 s24, v250, 28
	v_readlane_b32 s26, v250, 30
	v_readlane_b32 s28, v250, 32
	v_readlane_b32 s30, v250, 34
	v_readlane_b32 s17, v250, 21
	v_readlane_b32 s19, v250, 23
	v_readlane_b32 s21, v250, 25
	v_readlane_b32 s25, v250, 29
	v_readlane_b32 s27, v250, 31
	v_readlane_b32 s29, v250, 33
	v_readlane_b32 s31, v250, 35
	v_lshlrev_b32_e32 v54, 1, v29
	s_movk_i32 s8, 0xffbf
	s_movk_i32 s10, 0xffbe
	s_movk_i32 s12, 0xffbd
	s_movk_i32 s14, 0xffb0
	s_movk_i32 s16, 0xffaf
	s_movk_i32 s18, 0xffae
	s_movk_i32 s20, 0xffad
	s_movk_i32 s24, 0xff9f
	s_movk_i32 s26, 0xff9e
	s_movk_i32 s28, 0xff9d
	s_movk_i32 s30, 0xff90
	s_movk_i32 s34, 0xff8f
	s_movk_i32 s36, 0xff8e
	s_movk_i32 s38, 0xff8d
	s_mov_b32 s52, 0
	v_lshl_add_u64 v[68:69], v[66:67], 0, v[54:55]
	s_mov_b64 s[50:51], -1
	s_waitcnt vmcnt(1)
	ds_write_b128 v105, v[16:19] offset:18432
	s_waitcnt vmcnt(0)
	ds_write_b128 v105, v[20:23] offset:46080
	v_add_u32_e32 v16, 1, v28
	v_cvt_f32_ubyte0_e32 v16, v16
	v_mul_f32_e32 v17, -0.5, v16
	v_cmp_gt_f32_e32 vcc, s0, v17
	s_waitcnt lgkmcnt(0)
	s_barrier
	v_cndmask_b32_e32 v17, 0, v116, vcc
	v_fmac_f32_e32 v17, -0.5, v16
	v_exp_f32_e32 v16, v17
	v_cndmask_b32_e32 v17, 0, v117, vcc
	s_cselect_b64 s[0:1], -1, 0
	v_ldexp_f32 v16, v16, v17
	v_lshlrev_b32_e32 v17, 2, v28
	global_load_dword v17, v17, s[22:23]
	v_mul_f32_e32 v70, 0xbfb8aa3b, v16
	v_xor_b32_e32 v16, 16, v118
	s_and_b64 s[0:1], s[6:7], s[0:1]
	s_movk_i32 s6, 0xffc0
	s_movk_i32 s22, 0xffa0
	v_mov_b32_e32 v71, v70
	v_mov_b32_e32 v72, v70
	v_mov_b32_e32 v73, v70
	s_waitcnt vmcnt(0)
	v_mul_f32_e32 v120, 0x3fb8aa3b, v17
	v_and_b32_e32 v17, 64, v118
	v_add_u32_e32 v17, 64, v17
	v_cmp_lt_i32_e32 vcc, v16, v17
	s_nop 1
	v_cndmask_b32_e32 v16, v118, v16, vcc
	v_lshlrev_b32_e32 v121, 2, v16
	v_xor_b32_e32 v16, 32, v118
	v_cmp_lt_i32_e32 vcc, v16, v17
	s_nop 1
	v_cndmask_b32_e32 v16, v118, v16, vcc
	v_lshlrev_b32_e32 v122, 2, v16
	v_add_u32_e32 v16, s13, v109
	v_cmp_gt_i32_e64 s[6:7], s6, v16
	v_cmp_gt_i32_e64 s[8:9], s8, v16
	v_cmp_gt_i32_e64 s[10:11], s10, v16
	v_cmp_gt_i32_e64 s[12:13], s12, v16
	v_cmp_gt_i32_e64 s[14:15], s14, v16
	v_cmp_gt_i32_e64 s[16:17], s16, v16
	v_cmp_gt_i32_e64 s[18:19], s18, v16
	v_cmp_gt_i32_e64 s[20:21], s20, v16
	v_cmp_gt_i32_e64 s[22:23], s22, v16
	v_cmp_gt_i32_e64 s[24:25], s24, v16
	v_cmp_gt_i32_e64 s[26:27], s26, v16
	v_cmp_gt_i32_e64 s[28:29], s28, v16
	v_cmp_gt_i32_e64 s[30:31], s30, v16
	v_cmp_gt_i32_e64 s[34:35], s34, v16
	v_cmp_gt_i32_e64 s[36:37], s36, v16
	v_cmp_gt_i32_e64 s[38:39], s38, v16
	s_branch .LBB0_333

; #define LAS __attribute__((address_space(3)))
; __device__ __forceinline__ void lru_item(const Params& p, LAS unsigned char* L, int item, bool load_w) {
;     ...
;     if (load_w)
;     for (int idx = tid; idx < 192 * 24; idx += NTHR) {
;         const int r = idx / 24, g8 = idx % 24;
;         const bf16_t* src = (r < 96) ? WA + (size_t)(hf * 96 + r) * 192 + g8 * 8 : WI + (size_t)(hf * 96 + r - 96) * 192 + g8 * 8;
;         *(LAS u32x4*)(Wl + r * 200 + g8 * 8) = *(const u32x4*)src;
;     }
;     const bool cthr = tid < 384;
;     const int cgp = tid % 24, tq = (tid / 24) & 15;
;     const int chc = nb * 192 + cgp * 8;
;     if (load_w)
;     for (int idx = tid; idx < 5 * 192; idx += NTHR) { const int j = idx / 192, cc = idx % 192; CW[idx] = (j < 4) ? p.in[16][j * 1536 + nb * 192 + cc] : p.in[17][nb * 192 + cc]; }
.LBB0_1029:
	s_andn2_b64 vcc, exec, s[0:1]
	s_cbranch_vccnz .LBB0_1347
	s_lshl_b32 s0, s2, 4
	s_and_b32 s31, s0, 0x70
	s_lshr_b32 s0, s2, 4
	s_add_i32 s31, s31, s0
	s_bfe_u32 s30, s2, 0x10003
	s_lshl_b32 s29, s31, 1
	s_or_b32 s3, s29, s30
	s_add_i32 s4, s3, 0xffffff00
	s_cmpk_gt_u32 s31, 0x7f
	s_cselect_b64 s[16:17], -1, 0
	s_and_b64 s[0:1], s[16:17], exec
	s_cselect_b32 s10, s4, s3
	s_bfe_u32 s35, s10, 0x30001
	s_and_b32 s3, s10, 1
	s_mul_i32 s0, s35, 0x12000
	s_add_u32 s4, s44, s0
	s_addc_u32 s5, s45, 0
	s_add_u32 s0, s4, 0x1900000
	s_addc_u32 s1, s5, 0
	s_add_u32 s4, s4, 0x1990000
	s_mul_i32 s34, s3, 0x60
	s_addc_u32 s5, s5, 0
	s_add_i32 s11, s34, 0xffffffa0
	s_mov_b32 s12, 0xaaab
	s_movk_i32 s13, 0x8ff
	s_waitcnt lgkmcnt(0)
	v_mov_b32_e32 v1, 0
	v_mov_b32_e32 v2, v136
	v_mul_u32_u24_e32 v3, s12, v2
	v_lshrrev_b32_e32 v3, 20, v3
	v_mul_u32_u24_e32 v4, 24, v3
	v_sub_u32_e32 v4, v2, v4
	v_mul_u32_u24_e32 v50, 0x190, v3
	v_lshl_add_u32 v50, v4, 4, v50
	v_add_u32_e32 v5, s34, v3
	v_mul_u32_u24_e32 v5, 0x180, v5
	v_lshl_add_u32 v5, v4, 4, v5
	global_load_dwordx4 v[12:15], v5, s[0:1]
	v_add_u32_e32 v2, 0x200, v136
	v_mul_u32_u24_e32 v3, s12, v2
	v_lshrrev_b32_e32 v3, 20, v3
	v_mul_u32_u24_e32 v4, 24, v3
	v_sub_u32_e32 v4, v2, v4
	v_mul_u32_u24_e32 v51, 0x190, v3
	v_lshl_add_u32 v51, v4, 4, v51
	v_add_u32_e32 v5, s34, v3
	v_mul_u32_u24_e32 v5, 0x180, v5
	v_lshl_add_u32 v5, v4, 4, v5
	global_load_dwordx4 v[16:19], v5, s[0:1]
	v_add_u32_e32 v2, 0x400, v136
	v_mul_u32_u24_e32 v3, s12, v2
	v_lshrrev_b32_e32 v3, 20, v3
	v_mul_u32_u24_e32 v4, 24, v3
	v_sub_u32_e32 v4, v2, v4
	v_mul_u32_u24_e32 v52, 0x190, v3
	v_lshl_add_u32 v52, v4, 4, v52
	v_add_u32_e32 v5, s34, v3
	v_mul_u32_u24_e32 v5, 0x180, v5
	v_lshl_add_u32 v5, v4, 4, v5
	global_load_dwordx4 v[20:23], v5, s[0:1]
	v_add_u32_e32 v2, 0x600, v136
	v_mul_u32_u24_e32 v3, s12, v2
	v_lshrrev_b32_e32 v3, 20, v3
	v_mul_u32_u24_e32 v4, 24, v3
	v_sub_u32_e32 v4, v2, v4
	v_mul_u32_u24_e32 v53, 0x190, v3
	v_lshl_add_u32 v53, v4, 4, v53
	v_add_u32_e32 v5, s34, v3
	v_mul_u32_u24_e32 v5, 0x180, v5
	v_lshl_add_u32 v5, v4, 4, v5
	global_load_dwordx4 v[24:27], v5, s[0:1]
	v_add_u32_e32 v2, 0x800, v136
	v_mul_u32_u24_e32 v3, s12, v2
	v_lshrrev_b32_e32 v3, 20, v3
	v_mul_u32_u24_e32 v4, 24, v3
	v_sub_u32_e32 v4, v2, v4
	v_mul_u32_u24_e32 v54, 0x190, v3
	v_lshl_add_u32 v54, v4, 4, v54
	v_cmp_lt_u32_e32 vcc, s13, v2
	v_mov_b32_e32 v6, s34
	v_mov_b32_e32 v7, s11
	v_mov_b32_e32 v8, s0
	v_mov_b32_e32 v9, s1
	v_mov_b32_e32 v10, s4
	v_mov_b32_e32 v11, s5
	v_cndmask_b32_e32 v6, v6, v7, vcc
	v_cndmask_b32_e32 v8, v8, v10, vcc
	v_cndmask_b32_e32 v9, v9, v11, vcc
	v_add_u32_e32 v6, v6, v3
	v_mul_u32_u24_e32 v6, 0x180, v6
	v_lshl_add_u32 v6, v4, 4, v6
	v_mov_b32_e32 v7, 0
	v_lshl_add_u64 v[8:9], v[8:9], 0, v[6:7]
	global_load_dwordx4 v[28:31], v[8:9], off
	v_add_u32_e32 v2, 0xa00, v136
	v_mul_u32_u24_e32 v3, s12, v2
	v_lshrrev_b32_e32 v3, 20, v3
	v_mul_u32_u24_e32 v4, 24, v3
	v_sub_u32_e32 v4, v2, v4
	v_mul_u32_u24_e32 v55, 0x190, v3
	v_lshl_add_u32 v55, v4, 4, v55
	v_add_u32_e32 v5, s11, v3
	v_mul_u32_u24_e32 v5, 0x180, v5
	v_lshl_add_u32 v5, v4, 4, v5
	global_load_dwordx4 v[32:35], v5, s[4:5]
	v_add_u32_e32 v2, 0xc00, v136
	v_mul_u32_u24_e32 v3, s12, v2
	v_lshrrev_b32_e32 v3, 20, v3
	v_mul_u32_u24_e32 v4, 24, v3
	v_sub_u32_e32 v4, v2, v4
	v_mul_u32_u24_e32 v56, 0x190, v3
	v_lshl_add_u32 v56, v4, 4, v56
	v_add_u32_e32 v5, s11, v3
	v_mul_u32_u24_e32 v5, 0x180, v5
	v_lshl_add_u32 v5, v4, 4, v5
	global_load_dwordx4 v[36:39], v5, s[4:5]
	v_add_u32_e32 v2, 0xe00, v136
	v_mul_u32_u24_e32 v3, s12, v2
	v_lshrrev_b32_e32 v3, 20, v3
	v_mul_u32_u24_e32 v4, 24, v3
	v_sub_u32_e32 v4, v2, v4
	v_mul_u32_u24_e32 v57, 0x190, v3
	v_lshl_add_u32 v57, v4, 4, v57
	v_add_u32_e32 v5, s11, v3
	v_mul_u32_u24_e32 v5, 0x180, v5
	v_lshl_add_u32 v5, v4, 4, v5
	global_load_dwordx4 v[40:43], v5, s[4:5]
	v_add_u32_e32 v2, 0x1000, v136
	v_mul_u32_u24_e32 v3, s12, v2
	v_lshrrev_b32_e32 v3, 20, v3
	v_mul_u32_u24_e32 v4, 24, v3
	v_sub_u32_e32 v4, v2, v4
	v_mul_u32_u24_e32 v58, 0x190, v3
	v_lshl_add_u32 v58, v4, 4, v58
	v_add_u32_e32 v5, s11, v3
	v_mul_u32_u24_e32 v5, 0x180, v5
	v_lshl_add_u32 v5, v4, 4, v5
	global_load_dwordx4 v[44:47], v5, s[4:5]
	s_waitcnt vmcnt(0)
	ds_write_b128 v50, v[12:15]
	ds_write_b128 v51, v[16:19]
	ds_write_b128 v52, v[20:23]
	ds_write_b128 v53, v[24:27]
	ds_write_b128 v54, v[28:31]
	ds_write_b128 v55, v[32:35]
	ds_write_b128 v56, v[36:39]
	ds_write_b128 v57, v[40:43]
	ds_write_b128 v58, v[44:47]
	v_mov_b32_e32 v1, 0
	s_movk_i32 s0, 0x3c0
	s_mulk_i32 s35, 0xc0
	v_cmp_gt_u32_e32 vcc, s0, v136
	v_lshl_add_u32 v4, v136, 2, 0
	s_and_saveexec_b64 s[0:1], vcc
	s_cbranch_execz .LBB0_1043
	v_add_u32_e32 v5, 0x25f00, v4
	s_mov_b64 s[4:5], 0
	s_mov_b32 s8, 0xaaab
	s_movk_i32 s9, 0x2ff
	v_mov_b32_e32 v1, 0
	s_movk_i32 s11, 0x1bf
	v_mov_b32_e32 v6, v136
	s_branch .LBB0_1039

; #define LAS __attribute__((address_space(3)))
; __device__ __forceinline__ float bf2f(bf16_t b) { return __uint_as_float(((unsigned)b) << 16); }
; __device__ __forceinline__ float rcpf_(float x) { return __builtin_amdgcn_rcpf(x); }
; #define MFMA16(a, b, c) __builtin_amdgcn_mfma_f32_16x16x32_bf16((a), (b), (c), 0, 0, 0)
; __device__ __forceinline__ void lru_item(const Params& p, LAS unsigned char* L, int item, bool load_w) {
;     ...
; #pragma unroll 2
;         for (int ks = 0; ks < 6; ++ks) {
;             const bf16x8 uf = *(const LAS bf16x8*)(U + (mt * 16 + r16) * 200 + ks * 32 + q4 * 8);
; #pragma unroll
;             for (int cp = 0; cp < 3; ++cp) {
;                 const int ct = pg * 3 + cp;
;                 const bf16x8 wa = *(const LAS bf16x8*)(Wl + (ct * 16 + r16) * 200 + ks * 32 + q4 * 8), wi = *(const LAS bf16x8*)(Wl + (96 + ct * 16 + r16) * 200 + ks * 32 + q4 * 8);
;                 ga[cp] = MFMA16(uf, wa, ga[cp]); gi[cp] = MFMA16(uf, wi, gi[cp]);
;             }
;         }
; #pragma unroll
;         for (int cp = 0; cp < 3; ++cp) {
;             const int cl = (pg * 3 + cp) * 16 + r16;
; #pragma unroll
;             for (int jj = 0; jj < 4; ++jj) {
;                 const int t = mt * 16 + q4 * 4 + jj;
;                 const float rg = rcpf_(1.f + __builtin_amdgcn_exp2f(-(ga[cp][jj] + bra[cp]))), ig = rcpf_(1.f + __builtin_amdgcn_exp2f(-(gi[cp][jj] + bri[cp])));
;                 const float a = __builtin_amdgcn_exp2f(-(rg * spl[cp]));
;                 const float z2 = rg * sp[cp];
;                 const float om = (z2 < 0.05f) ? z2 * (1.f - z2 * (0.5f - z2 * (0.16666667f - z2 * 0.041666668f))) : 1.f - a * a;
;                 const float uu = bf2f(U[t * 200 + hf * 96 + cl]);
;                 Aa[t * 96 + cl] = a; Bb[t * 96 + cl] = __builtin_amdgcn_sqrtf(om) * ig * uu;
;             }
;         }
.LBB0_1094:
	v_add_u32_e32 v32, s0, v156
	v_add_u32_e32 v198, s0, v155
	v_add_u32_e32 v74, 0x12c00, v32
	ds_read_b128 v[66:69], v198
	ds_read_b128 v[70:73], v198 offset:51264
	ds_read_b128 v[74:77], v74
	ds_read_b128 v[78:81], v198 offset:38400
	v_add_u32_e32 v32, 0x12c40, v32
	s_addk_i32 s0, 0x80
	s_waitcnt lgkmcnt(1)
	v_mfma_f32_16x16x32_bf16 v[62:65], v[74:77], v[66:69], v[62:65]
	s_cmpk_lg_i32 s0, 0x180
	s_waitcnt lgkmcnt(0)
	v_mfma_f32_16x16x32_bf16 v[58:61], v[74:77], v[78:81], v[58:61]
	ds_read_b128 v[66:69], v198 offset:6400
	ds_read_b128 v[78:81], v198 offset:64
	s_waitcnt lgkmcnt(1)
	v_mfma_f32_16x16x32_bf16 v[54:57], v[74:77], v[66:69], v[54:57]
	ds_read_b128 v[66:69], v198 offset:44800
	ds_read_b128 v[82:85], v198 offset:38464
	s_waitcnt lgkmcnt(1)
	v_mfma_f32_16x16x32_bf16 v[50:53], v[74:77], v[66:69], v[50:53]
	ds_read_b128 v[66:69], v198 offset:12800
	ds_read_b128 v[86:89], v198 offset:6464
	ds_read_b128 v[90:93], v198 offset:44864
	s_waitcnt lgkmcnt(2)
	v_mfma_f32_16x16x32_bf16 v[46:49], v[74:77], v[66:69], v[46:49]
	ds_read_b128 v[66:69], v198 offset:51200
	s_waitcnt lgkmcnt(0)
	v_mfma_f32_16x16x32_bf16 v[42:45], v[74:77], v[66:69], v[42:45]
	ds_read_b128 v[66:69], v32
	ds_read_b128 v[74:77], v198 offset:12864
	s_waitcnt lgkmcnt(1)
	v_mfma_f32_16x16x32_bf16 v[62:65], v[66:69], v[78:81], v[62:65]
	v_mfma_f32_16x16x32_bf16 v[58:61], v[66:69], v[82:85], v[58:61]
	v_mfma_f32_16x16x32_bf16 v[54:57], v[66:69], v[86:89], v[54:57]
	v_mfma_f32_16x16x32_bf16 v[50:53], v[66:69], v[90:93], v[50:53]
	s_waitcnt lgkmcnt(0)
	v_mfma_f32_16x16x32_bf16 v[46:49], v[66:69], v[74:77], v[46:49]
	v_mfma_f32_16x16x32_bf16 v[42:45], v[66:69], v[70:73], v[42:45]
	s_cbranch_scc1 .LBB0_1094
	s_nop 0
	v_add_f32_e32 v32, v178, v62
	v_exp_f32_e64 v32, -v32
	s_nop 0
	v_add_f32_e32 v32, 1.0, v32
	v_rcp_f32_e32 v62, v32
	s_nop 0
	v_mul_f32_e32 v32, v191, v62
	v_exp_f32_e32 v32, v32
	v_mul_f32_e32 v66, v180, v62
	v_cmp_ngt_f32_e32 vcc, s49, v66
	s_and_saveexec_b64 s[0:1], vcc
	s_xor_b64 s[0:1], exec, s[0:1]
	v_fma_f32 v62, -v32, v32, 1.0
	s_andn2_saveexec_b64 s[0:1], s[0:1]
	v_fmamk_f32 v62, v66, 0xbd2aaaab, v194
	v_fma_f32 v62, -v66, v62, 0.5
	v_fma_f32 v62, -v66, v62, 1.0
	v_mul_f32_e32 v62, v66, v62
	s_or_b64 exec, exec, s[0:1]
	v_add_f32_e32 v58, v179, v58
	v_exp_f32_e64 v58, -v58
	v_add_f32_e32 v63, v178, v63
	v_exp_f32_e64 v63, -v63
	ds_read_u16 v66, v195
	v_add_f32_e32 v58, 1.0, v58
	v_rcp_f32_e32 v58, v58
	v_sqrt_f32_e32 v62, v62
	v_add_f32_e32 v63, 1.0, v63
	v_rcp_f32_e32 v63, v63
	s_waitcnt lgkmcnt(0)
	v_lshlrev_b32_e32 v66, 16, v66
	ds_write_b32 v153, v32
	v_mul_f32_e32 v32, v58, v62
	v_mul_f32_e32 v58, v32, v66
	v_mul_f32_e32 v32, v191, v63
	v_exp_f32_e32 v32, v32
	v_mul_f32_e32 v62, v180, v63
	v_cmp_ngt_f32_e32 vcc, s49, v62
	ds_write_b32 v152, v58
	s_and_saveexec_b64 s[0:1], vcc
	s_xor_b64 s[0:1], exec, s[0:1]
	v_fma_f32 v58, -v32, v32, 1.0
	s_andn2_saveexec_b64 s[0:1], s[0:1]
	v_fmamk_f32 v58, v62, 0xbd2aaaab, v194
	v_fma_f32 v58, -v62, v58, 0.5
	v_fma_f32 v58, -v62, v58, 1.0
	v_mul_f32_e32 v58, v62, v58
	s_or_b64 exec, exec, s[0:1]
	v_add_f32_e32 v59, v179, v59
	v_exp_f32_e64 v59, -v59
	v_add_f32_e32 v63, v178, v64
	v_exp_f32_e64 v63, -v63
	ds_read_u16 v62, v195 offset:400
	v_add_f32_e32 v59, 1.0, v59
	v_rcp_f32_e32 v59, v59
	v_sqrt_f32_e32 v58, v58
	v_add_f32_e32 v63, 1.0, v63
	v_rcp_f32_e32 v63, v63
	s_waitcnt lgkmcnt(0)
	v_lshlrev_b32_e32 v62, 16, v62
	ds_write_b32 v150, v32
	v_mul_f32_e32 v32, v59, v58
	v_mul_f32_e32 v58, v32, v62
	v_mul_f32_e32 v32, v191, v63
	v_exp_f32_e32 v32, v32
	v_mul_f32_e32 v59, v180, v63
	v_cmp_ngt_f32_e32 vcc, s49, v59
	ds_write_b32 v149, v58
	s_and_saveexec_b64 s[0:1], vcc
	s_xor_b64 s[0:1], exec, s[0:1]
	v_fma_f32 v58, -v32, v32, 1.0
	s_andn2_saveexec_b64 s[0:1], s[0:1]
	v_fmamk_f32 v58, v59, 0xbd2aaaab, v194
	v_fma_f32 v58, -v59, v58, 0.5
	v_fma_f32 v58, -v59, v58, 1.0
	v_mul_f32_e32 v58, v59, v58
	s_or_b64 exec, exec, s[0:1]
	v_add_f32_e32 v59, v179, v60
	v_exp_f32_e64 v59, -v59
	v_add_f32_e32 v62, v178, v65
	v_exp_f32_e64 v62, -v62
	ds_read_u16 v60, v195 offset:800
	v_add_f32_e32 v59, 1.0, v59
	v_rcp_f32_e32 v59, v59
	v_sqrt_f32_e32 v58, v58
	v_add_f32_e32 v62, 1.0, v62
	v_rcp_f32_e32 v62, v62
	s_waitcnt lgkmcnt(0)
	v_lshlrev_b32_e32 v60, 16, v60
	ds_write_b32 v148, v32
	v_mul_f32_e32 v32, v59, v58
	v_mul_f32_e32 v58, v32, v60
	v_mul_f32_e32 v32, v191, v62
	v_exp_f32_e32 v32, v32
	v_mul_f32_e32 v59, v180, v62
	v_cmp_ngt_f32_e32 vcc, s49, v59
	ds_write_b32 v147, v58
	s_and_saveexec_b64 s[0:1], vcc
	s_xor_b64 s[0:1], exec, s[0:1]
	v_fma_f32 v58, -v32, v32, 1.0
	s_andn2_saveexec_b64 s[0:1], s[0:1]
	v_fmamk_f32 v58, v59, 0xbd2aaaab, v194
	v_fma_f32 v58, -v59, v58, 0.5
	v_fma_f32 v58, -v59, v58, 1.0
	v_mul_f32_e32 v58, v59, v58
	s_or_b64 exec, exec, s[0:1]
	v_add_f32_e32 v59, v179, v61
	v_exp_f32_e64 v59, -v59
	v_add_f32_e32 v54, v181, v54
	v_exp_f32_e64 v54, -v54
	ds_read_u16 v60, v195 offset:1200
	v_add_f32_e32 v59, 1.0, v59
	v_rcp_f32_e32 v59, v59
	v_sqrt_f32_e32 v58, v58
	v_add_f32_e32 v54, 1.0, v54
	v_rcp_f32_e32 v54, v54
	s_waitcnt lgkmcnt(0)
	v_lshlrev_b32_e32 v60, 16, v60
	ds_write_b32 v146, v32
	v_mul_f32_e32 v32, v59, v58
	v_mul_f32_e32 v58, v32, v60
	v_mul_f32_e32 v32, v192, v54
	v_exp_f32_e32 v32, v32
	ds_write_b32 v145, v58
	v_mul_f32_e32 v58, v183, v54
	v_cmp_ngt_f32_e32 vcc, s49, v58
	s_and_saveexec_b64 s[0:1], vcc
	s_xor_b64 s[0:1], exec, s[0:1]
	v_fma_f32 v54, -v32, v32, 1.0
	s_andn2_saveexec_b64 s[0:1], s[0:1]
	v_fmamk_f32 v54, v58, 0xbd2aaaab, v194
	v_fma_f32 v54, -v58, v54, 0.5
	v_fma_f32 v54, -v58, v54, 1.0
	v_mul_f32_e32 v54, v58, v54
	s_or_b64 exec, exec, s[0:1]
	v_add_f32_e32 v50, v182, v50
	v_exp_f32_e64 v50, -v50
	v_add_f32_e32 v55, v181, v55
	v_exp_f32_e64 v55, -v55
	ds_read_u16 v58, v196 offset:32
	v_add_f32_e32 v50, 1.0, v50
	v_rcp_f32_e32 v50, v50
	v_sqrt_f32_e32 v54, v54
	v_add_f32_e32 v55, 1.0, v55
	v_rcp_f32_e32 v55, v55
	s_waitcnt lgkmcnt(0)
; __device__ __forceinline__ float bf2f(bf16_t b) { return __uint_as_float(((unsigned)b) << 16); }
; __device__ __forceinline__ float rcpf_(float x) { return __builtin_amdgcn_rcpf(x); }
; __device__ __forceinline__ void lds_barrier() { asm volatile("s_waitcnt lgkmcnt(0)" ::: "memory"); __builtin_amdgcn_s_barrier(); asm volatile("" ::: "memory"); }
; __device__ __forceinline__ void lru_item(const Params& p, LAS unsigned char* L, int item, bool load_w) {
;     ...
;         for (int cp = 0; cp < 3; ++cp) {
;             const int cl = (pg * 3 + cp) * 16 + r16;
; #pragma unroll
;             for (int jj = 0; jj < 4; ++jj) {
;                 const int t = mt * 16 + q4 * 4 + jj;
;                 const float rg = rcpf_(1.f + __builtin_amdgcn_exp2f(-(ga[cp][jj] + bra[cp]))), ig = rcpf_(1.f + __builtin_amdgcn_exp2f(-(gi[cp][jj] + bri[cp])));
;                 const float a = __builtin_amdgcn_exp2f(-(rg * spl[cp]));
;                 const float z2 = rg * sp[cp];
;                 const float om = (z2 < 0.05f) ? z2 * (1.f - z2 * (0.5f - z2 * (0.16666667f - z2 * 0.041666668f))) : 1.f - a * a;
;                 const float uu = bf2f(U[t * 200 + hf * 96 + cl]);
;                 Aa[t * 96 + cl] = a; Bb[t * 96 + cl] = __builtin_amdgcn_sqrtf(om) * ig * uu;
;             }
;         }
;         lds_barrier();
	v_lshlrev_b32_e32 v58, 16, v58
	ds_write_b32 v144, v32
	v_mul_f32_e32 v32, v50, v54
	v_mul_f32_e32 v50, v32, v58
	v_mul_f32_e32 v32, v192, v55
	v_exp_f32_e32 v32, v32
	v_mul_f32_e32 v54, v183, v55
	v_cmp_ngt_f32_e32 vcc, s49, v54
	ds_write_b32 v143, v50
	s_and_saveexec_b64 s[0:1], vcc
	s_xor_b64 s[0:1], exec, s[0:1]
	v_fma_f32 v50, -v32, v32, 1.0
	s_andn2_saveexec_b64 s[0:1], s[0:1]
	v_fmamk_f32 v50, v54, 0xbd2aaaab, v194
	v_fma_f32 v50, -v54, v50, 0.5
	v_fma_f32 v50, -v54, v50, 1.0
	v_mul_f32_e32 v50, v54, v50
	s_or_b64 exec, exec, s[0:1]
	v_add_f32_e32 v51, v182, v51
	v_exp_f32_e64 v51, -v51
	v_add_f32_e32 v55, v181, v56
	v_exp_f32_e64 v55, -v55
	ds_read_u16 v54, v196 offset:432
	v_add_f32_e32 v51, 1.0, v51
	v_rcp_f32_e32 v51, v51
	v_sqrt_f32_e32 v50, v50
	v_add_f32_e32 v55, 1.0, v55
	v_rcp_f32_e32 v55, v55
	s_waitcnt lgkmcnt(0)
	v_lshlrev_b32_e32 v54, 16, v54
	ds_write_b32 v142, v32
	v_mul_f32_e32 v32, v51, v50
	v_mul_f32_e32 v50, v32, v54
	v_mul_f32_e32 v32, v192, v55
	v_exp_f32_e32 v32, v32
	v_mul_f32_e32 v51, v183, v55
	v_cmp_ngt_f32_e32 vcc, s49, v51
	ds_write_b32 v141, v50
	s_and_saveexec_b64 s[0:1], vcc
	s_xor_b64 s[0:1], exec, s[0:1]
	v_fma_f32 v50, -v32, v32, 1.0
	s_andn2_saveexec_b64 s[0:1], s[0:1]
	v_fmamk_f32 v50, v51, 0xbd2aaaab, v194
	v_fma_f32 v50, -v51, v50, 0.5
	v_fma_f32 v50, -v51, v50, 1.0
	v_mul_f32_e32 v50, v51, v50
	s_or_b64 exec, exec, s[0:1]
	v_add_f32_e32 v51, v182, v52
	v_exp_f32_e64 v51, -v51
	v_add_f32_e32 v54, v181, v57
	v_exp_f32_e64 v54, -v54
	ds_read_u16 v52, v196 offset:832
	v_add_f32_e32 v51, 1.0, v51
	v_rcp_f32_e32 v51, v51
	v_sqrt_f32_e32 v50, v50
	v_add_f32_e32 v54, 1.0, v54
	v_rcp_f32_e32 v54, v54
	s_waitcnt lgkmcnt(0)
	v_lshlrev_b32_e32 v52, 16, v52
	ds_write_b32 v140, v32
	v_mul_f32_e32 v32, v51, v50
	v_mul_f32_e32 v50, v32, v52
	v_mul_f32_e32 v32, v192, v54
	v_exp_f32_e32 v32, v32
	v_mul_f32_e32 v51, v183, v54
	v_cmp_ngt_f32_e32 vcc, s49, v51
	ds_write_b32 v139, v50
	s_and_saveexec_b64 s[0:1], vcc
	s_xor_b64 s[0:1], exec, s[0:1]
	v_fma_f32 v50, -v32, v32, 1.0
	s_andn2_saveexec_b64 s[0:1], s[0:1]
	v_fmamk_f32 v50, v51, 0xbd2aaaab, v194
	v_fma_f32 v50, -v51, v50, 0.5
	v_fma_f32 v50, -v51, v50, 1.0
	v_mul_f32_e32 v50, v51, v50
	s_or_b64 exec, exec, s[0:1]
	v_add_f32_e32 v51, v182, v53
	v_exp_f32_e64 v51, -v51
	v_add_f32_e32 v46, v184, v46
	v_exp_f32_e64 v46, -v46
	ds_read_u16 v52, v196 offset:1232
	v_add_f32_e32 v51, 1.0, v51
	v_rcp_f32_e32 v51, v51
	v_sqrt_f32_e32 v50, v50
	v_add_f32_e32 v46, 1.0, v46
	v_rcp_f32_e32 v46, v46
	s_waitcnt lgkmcnt(0)
	v_lshlrev_b32_e32 v52, 16, v52
	ds_write_b32 v138, v32
	v_mul_f32_e32 v32, v51, v50
	v_mul_f32_e32 v50, v32, v52
	v_mul_f32_e32 v32, v193, v46
	v_exp_f32_e32 v32, v32
	ds_write_b32 v137, v50
	v_mul_f32_e32 v50, v186, v46
	v_cmp_ngt_f32_e32 vcc, s49, v50
	s_and_saveexec_b64 s[0:1], vcc
	s_xor_b64 s[0:1], exec, s[0:1]
	v_fma_f32 v46, -v32, v32, 1.0
	s_andn2_saveexec_b64 s[0:1], s[0:1]
	v_fmamk_f32 v46, v50, 0xbd2aaaab, v194
	v_fma_f32 v46, -v50, v46, 0.5
	v_fma_f32 v46, -v50, v46, 1.0
	v_mul_f32_e32 v46, v50, v46
	s_or_b64 exec, exec, s[0:1]
	v_add_f32_e32 v42, v185, v42
	v_exp_f32_e64 v42, -v42
	v_add_f32_e32 v47, v184, v47
	v_exp_f32_e64 v47, -v47
	ds_read_u16 v50, v196 offset:64
	v_add_f32_e32 v42, 1.0, v42
	v_rcp_f32_e32 v42, v42
	v_sqrt_f32_e32 v46, v46
	v_add_f32_e32 v47, 1.0, v47
	v_rcp_f32_e32 v47, v47
	s_waitcnt lgkmcnt(0)
	v_lshlrev_b32_e32 v50, 16, v50
	ds_write_b32 v135, v32
	v_mul_f32_e32 v32, v42, v46
	v_mul_f32_e32 v42, v32, v50
	v_mul_f32_e32 v32, v193, v47
	v_exp_f32_e32 v32, v32
	v_mul_f32_e32 v46, v186, v47
	v_cmp_ngt_f32_e32 vcc, s49, v46
	ds_write_b32 v134, v42
	s_and_saveexec_b64 s[0:1], vcc
	s_xor_b64 s[0:1], exec, s[0:1]
	v_fma_f32 v42, -v32, v32, 1.0
	s_andn2_saveexec_b64 s[0:1], s[0:1]
	v_fmamk_f32 v42, v46, 0xbd2aaaab, v194
	v_fma_f32 v42, -v46, v42, 0.5
	v_fma_f32 v42, -v46, v42, 1.0
	v_mul_f32_e32 v42, v46, v42
	s_or_b64 exec, exec, s[0:1]
	v_add_f32_e32 v43, v185, v43
	v_exp_f32_e64 v43, -v43
	v_add_f32_e32 v47, v184, v48
	v_exp_f32_e64 v47, -v47
	ds_read_u16 v46, v196 offset:464
	v_add_f32_e32 v43, 1.0, v43
	v_rcp_f32_e32 v43, v43
	v_sqrt_f32_e32 v42, v42
	v_add_f32_e32 v47, 1.0, v47
	v_rcp_f32_e32 v47, v47
	s_waitcnt lgkmcnt(0)
	v_lshlrev_b32_e32 v46, 16, v46
	ds_write_b32 v133, v32
	v_mul_f32_e32 v32, v43, v42
	v_mul_f32_e32 v42, v32, v46
	v_mul_f32_e32 v32, v193, v47
	v_exp_f32_e32 v32, v32
	v_mul_f32_e32 v43, v186, v47
	v_cmp_ngt_f32_e32 vcc, s49, v43
	ds_write_b32 v132, v42
	s_and_saveexec_b64 s[0:1], vcc
	s_xor_b64 s[0:1], exec, s[0:1]
	v_fma_f32 v42, -v32, v32, 1.0
	s_andn2_saveexec_b64 s[0:1], s[0:1]
	v_fmamk_f32 v42, v43, 0xbd2aaaab, v194
	v_fma_f32 v42, -v43, v42, 0.5
	v_fma_f32 v42, -v43, v42, 1.0
	v_mul_f32_e32 v42, v43, v42
	s_or_b64 exec, exec, s[0:1]
	v_add_f32_e32 v43, v185, v44
	v_exp_f32_e64 v43, -v43
	v_add_f32_e32 v46, v184, v49
	v_exp_f32_e64 v46, -v46
	ds_read_u16 v44, v196 offset:864
	v_add_f32_e32 v43, 1.0, v43
	v_rcp_f32_e32 v43, v43
	v_sqrt_f32_e32 v42, v42
	v_add_f32_e32 v46, 1.0, v46
	v_rcp_f32_e32 v46, v46
	s_waitcnt lgkmcnt(0)
	v_lshlrev_b32_e32 v44, 16, v44
	ds_write_b32 v131, v32
	v_mul_f32_e32 v32, v43, v42
	v_mul_f32_e32 v42, v32, v44
	v_mul_f32_e32 v32, v193, v46
	v_exp_f32_e32 v32, v32
	v_mul_f32_e32 v43, v186, v46
	v_cmp_ngt_f32_e32 vcc, s49, v43
	ds_write_b32 v130, v42
	s_and_saveexec_b64 s[0:1], vcc
	s_xor_b64 s[0:1], exec, s[0:1]
	v_fma_f32 v42, -v32, v32, 1.0
	s_andn2_saveexec_b64 s[0:1], s[0:1]
	v_fmamk_f32 v42, v43, 0xbd2aaaab, v194
	v_fma_f32 v42, -v43, v42, 0.5
	v_fma_f32 v42, -v43, v42, 1.0
	v_mul_f32_e32 v42, v43, v42
	s_or_b64 exec, exec, s[0:1]
	v_add_f32_e32 v43, v185, v45
	v_exp_f32_e64 v43, -v43
	ds_read_u16 v44, v196 offset:1264
	v_sqrt_f32_e32 v42, v42
	ds_write_b32 v129, v32
	v_add_f32_e32 v43, 1.0, v43
	v_rcp_f32_e32 v43, v43
	s_waitcnt lgkmcnt(1)
	v_lshlrev_b32_e32 v32, 16, v44
	v_mul_f32_e32 v42, v43, v42
	v_mul_f32_e32 v32, v42, v32
	ds_write_b32 v128, v32
	s_waitcnt lgkmcnt(0)
	s_barrier
; __device__ __forceinline__ void lru_item(const Params& p, LAS unsigned char* L, int item, bool load_w) {
;     ...
;         if (cthr) {
;             float P = 1.f, H = 0.f;
; #pragma unroll
;             for (int t = 0; t < 16; ++t) {
;                 const int ix = (sseg * 16 + t) * 96 + sch;
;                 const float a = Aa[ix]; H = a * H + Bb[ix]; P *= a; Aa[ix] = P; Bb[ix] = H;
;             }
;             SP[sseg * 96 + sch] = P; SH[sseg * 96 + sch] = H;
;         }
	s_and_saveexec_b64 s[0:1], s[8:9]
	s_cbranch_execz .LBB0_1145
	v_mul_lo_u32 v32, v197, s48
	v_add_lshl_u32 v32, v32, v118, 2
	v_add_u32_e32 v50, s28, v32
	v_add_u32_e32 v51, s3, v32
	ds_read_b32 v198, v50
	ds_read_b32 v214, v51
	ds_read_b32 v199, v50 offset:384
	ds_read_b32 v215, v51 offset:384
	ds_read_b32 v200, v50 offset:768
	ds_read_b32 v216, v51 offset:768
	ds_read_b32 v201, v50 offset:1152
	ds_read_b32 v217, v51 offset:1152
	ds_read_b32 v202, v50 offset:1536
	ds_read_b32 v218, v51 offset:1536
	ds_read_b32 v203, v50 offset:1920
	ds_read_b32 v219, v51 offset:1920
	ds_read_b32 v204, v50 offset:2304
	ds_read_b32 v220, v51 offset:2304
	ds_read_b32 v205, v50 offset:2688
	ds_read_b32 v221, v51 offset:2688
	ds_read_b32 v206, v50 offset:3072
	ds_read_b32 v222, v51 offset:3072
	ds_read_b32 v207, v50 offset:3456
	ds_read_b32 v223, v51 offset:3456
	ds_read_b32 v208, v50 offset:3840
	ds_read_b32 v224, v51 offset:3840
	ds_read_b32 v209, v50 offset:4224
	ds_read_b32 v225, v51 offset:4224
	ds_read_b32 v210, v50 offset:4608
	ds_read_b32 v226, v51 offset:4608
	ds_read_b32 v211, v50 offset:4992
	ds_read_b32 v227, v51 offset:4992
	ds_read_b32 v212, v50 offset:5376
	ds_read_b32 v228, v51 offset:5376
	ds_read_b32 v213, v50 offset:5760
	ds_read_b32 v229, v51 offset:5760
	v_mad_u32_u24 v42, v197, s33, v118
	v_lshl_add_u32 v32, v42, 2, 0
	v_add_u32_e32 v42, 0x25000, v32
	v_add_u32_e32 v32, 0x25600, v32
	s_waitcnt lgkmcnt(15)
	v_fmac_f32_e32 v214, 0, v198
	v_fmac_f32_e32 v215, v214, v199
	v_mul_f32_e32 v199, v198, v199
	v_fmac_f32_e32 v216, v215, v200
	v_mul_f32_e32 v200, v199, v200
	v_fmac_f32_e32 v217, v216, v201
	v_mul_f32_e32 v201, v200, v201
	v_fmac_f32_e32 v218, v217, v202
	v_mul_f32_e32 v202, v201, v202
	v_fmac_f32_e32 v219, v218, v203
	v_mul_f32_e32 v203, v202, v203
	v_fmac_f32_e32 v220, v219, v204
	v_mul_f32_e32 v204, v203, v204
	v_fmac_f32_e32 v221, v220, v205
	v_mul_f32_e32 v205, v204, v205
	s_waitcnt lgkmcnt(0)
	v_fmac_f32_e32 v222, v221, v206
	v_mul_f32_e32 v206, v205, v206
	v_fmac_f32_e32 v223, v222, v207
	v_mul_f32_e32 v207, v206, v207
	v_fmac_f32_e32 v224, v223, v208
	v_mul_f32_e32 v208, v207, v208
	v_fmac_f32_e32 v225, v224, v209
	v_mul_f32_e32 v209, v208, v209
	v_fmac_f32_e32 v226, v225, v210
	v_mul_f32_e32 v210, v209, v210
	v_fmac_f32_e32 v227, v226, v211
	v_mul_f32_e32 v211, v210, v211
	v_fmac_f32_e32 v228, v227, v212
	v_mul_f32_e32 v212, v211, v212
	v_fmac_f32_e32 v229, v228, v213
	v_mul_f32_e32 v213, v212, v213
	ds_write_b32 v51, v214
	ds_write_b32 v50, v199 offset:384
	ds_write_b32 v51, v215 offset:384
	ds_write_b32 v50, v200 offset:768
	ds_write_b32 v51, v216 offset:768
	ds_write_b32 v50, v201 offset:1152
	ds_write_b32 v51, v217 offset:1152
	ds_write_b32 v50, v202 offset:1536
	ds_write_b32 v51, v218 offset:1536
	ds_write_b32 v50, v203 offset:1920
	ds_write_b32 v51, v219 offset:1920
	ds_write_b32 v50, v204 offset:2304
	ds_write_b32 v51, v220 offset:2304
	ds_write_b32 v50, v205 offset:2688
	ds_write_b32 v51, v221 offset:2688
	ds_write_b32 v50, v206 offset:3072
	ds_write_b32 v51, v222 offset:3072
	ds_write_b32 v50, v207 offset:3456
	ds_write_b32 v51, v223 offset:3456
	ds_write_b32 v50, v208 offset:3840
	ds_write_b32 v51, v224 offset:3840
	ds_write_b32 v50, v209 offset:4224
	ds_write_b32 v51, v225 offset:4224
	ds_write_b32 v50, v210 offset:4608
	ds_write_b32 v51, v226 offset:4608
	ds_write_b32 v50, v211 offset:4992
	ds_write_b32 v51, v227 offset:4992
	ds_write_b32 v50, v212 offset:5376
	ds_write_b32 v51, v228 offset:5376
	ds_write_b32 v50, v213 offset:5760
	ds_write_b32 v51, v229 offset:5760
	ds_write_b32 v42, v213
	ds_write_b32 v32, v229
